# P6 tile order: each XCD owns 4 token tiles, all XCDs sweep the same 8 weight tiles per round (B tiles shared through MALL); on top of v9
# speedup vs baseline: 1.0011x; 1.0011x over previous
.LBB0_724:
	s_cmp_lt_i32 s36, 7
	s_cselect_b64 s[2:3], -1, 0
	s_and_b64 s[2:3], s[2:3], s[0:1]
	s_andn2_b64 vcc, exec, s[2:3]
	s_cbranch_vccnz .LBB0_801
	s_cmpk_lt_i32 s94, 0xc18
	s_cselect_b64 s[0:1], -1, 0
	s_cmpk_gt_i32 s94, 0xc17
	v_readfirstlane_b32 s26, v0
	s_cbranch_scc1 .LBB0_795
	s_add_u32 s27, s80, 0x11a00000
	s_addc_u32 s28, s81, 0
	s_add_u32 s29, s80, 0x1800000
	s_addc_u32 s30, s81, 0
	s_lshr_b32 s16, s26, 6
	s_lshr_b32 s17, s26, 8
	s_lshl_b32 s31, s16, 10
	s_and_b64 s[0:1], s[0:1], exec
	s_cselect_b32 s0, s94, 0
	s_ashr_i32 s1, s0, 31
	s_lshr_b32 s1, s1, 29
	s_add_i32 s1, s0, s1
	s_ashr_i32 s4, s1, 3
	s_and_b32 s1, s1, -8
	s_sub_i32 s0, s0, s1
	s_cmp_lt_i32 s0, 0
	s_movk_i32 s33, 0x184
	s_cselect_b32 s1, s33, 0x183
	s_mul_i32 s0, s0, s1
	s_add_i32 s0, s0, s4
	s_mul_hi_i32 s1, s0, 0x2fa0be83
	s_lshr_b32 s4, s1, 31
	s_ashr_i32 s1, s1, 7
	s_add_i32 s1, s1, s4
	s_lshl_b32 s4, s1, 3
	s_sub_i32 s5, 36, s4
	s_min_u32 s5, s5, 8
	s_mulk_i32 s1, 0x2b0
	s_sub_i32 s6, s0, s1
	s_waitcnt vmcnt(0)
	v_cvt_f32_ubyte0_e32 v2, s5
	v_cvt_f32_i32_e32 v1, s6
	v_rcp_iflag_f32_e32 v3, v2
	s_ashr_i32 s0, s6, 30
	s_or_b32 s7, s0, 1
	v_or_b32_e32 v10, 0x2000, v134
	v_mul_f32_e32 v3, v1, v3
	v_trunc_f32_e32 v3, v3
	v_fma_f32 v1, -v3, v2, v1
	v_cvt_i32_f32_e32 v3, v3
	v_cmp_ge_f32_e64 s[0:1], |v1|, v2
	s_and_b64 s[0:1], s[0:1], exec
	s_cselect_b32 s0, s7, 0
	v_readfirstlane_b32 s1, v3
	s_add_i32 s0, s1, s0
	s_mul_i32 s1, s0, s5
	s_sub_i32 s1, s6, s1
	v_lshrrev_b32_e32 v1, 5, v0
	v_lshrrev_b32_e32 v3, 1, v0
	s_sext_i32_i16 s1, s1
	v_and_b32_e32 v1, 4, v1
	v_bfe_u32 v2, v0, 2, 2
	v_and_b32_e32 v13, 24, v3
	s_add_i32 s4, s4, s1
	s_and_b32 s4, s94, 7
	s_lshl_b32 s4, s4, 2
	s_lshr_b32 s0, s94, 3
	s_and_b32 s1, s0, 3
	s_add_i32 s4, s4, s1
	s_lshr_b32 s0, s0, 2
	v_or3_b32 v1, v1, v2, v13
	v_lshrrev_b32_e32 v2, 7, v10
	s_movk_i32 s1, 0x60
	v_and_or_b32 v3, v2, s1, v1
	v_and_b32_e32 v4, 32, v0
	s_movk_i32 s1, 0x70
	v_bitop3_b32 v11, v134, v4, 48 bitop3:0x6c
	v_and_b32_e32 v12, 64, v0
	v_bfe_u32 v14, v0, 2, 4
	s_ashr_i32 s5, s4, 31
	s_bfe_i64 s[8:9], s[0:1], 0x100000
	v_or_b32_e32 v4, v11, v12
	v_and_or_b32 v2, v2, s1, v14
	s_lshl_b64 s[6:7], s[4:5], 21
	s_lshl_b64 s[8:9], s[8:9], 21
	v_lshl_or_b32 v132, v2, 13, v4
	v_lshrrev_b32_e32 v2, 3, v0
	s_add_u32 s12, s29, s8
	v_and_or_b32 v1, v2, 32, v1
	s_addc_u32 s13, s30, s9
	s_add_i32 s34, s31, 0
	v_lshl_or_b32 v136, v1, 13, v4
	s_add_i32 m0, s34, 0x10000
	v_lshl_or_b32 v130, v3, 13, v4
	global_load_lds_dwordx4 v136, s[12:13]
	s_add_i32 m0, s34, 0x12000
	s_add_u32 s14, s27, s6
	s_addc_u32 s15, s28, s7
	s_add_u32 s6, s12, 0x100000
	global_load_lds_dwordx4 v130, s[12:13]
	s_addc_u32 s7, s13, 0
	s_add_i32 m0, s34, 0x14000
	v_and_or_b32 v1, v2, 48, v14
	global_load_lds_dwordx4 v136, s[6:7]
	s_add_i32 m0, s34, 0x16000
	s_add_i32 s35, s34, 0x2000
	v_lshl_or_b32 v138, v1, 13, v4
	global_load_lds_dwordx4 v130, s[6:7]
	s_mov_b32 m0, s34
	s_add_u32 s6, s14, 0x100000
	global_load_lds_dwordx4 v138, s[14:15]
	s_mov_b32 m0, s35
	s_addc_u32 s7, s15, 0
	s_add_i32 s36, s34, 0x4000
	global_load_lds_dwordx4 v132, s[14:15]
	s_mov_b32 m0, s36
	s_add_i32 s37, s34, 0x6000
	global_load_lds_dwordx4 v138, s[6:7]
	s_mov_b32 m0, s37
	v_mov_b32_e32 v137, 0
	global_load_lds_dwordx4 v132, s[6:7]
	v_mov_b32_e32 v131, v137
	v_mov_b32_e32 v139, v137
	v_mov_b32_e32 v133, v137
	s_mov_b32 s38, 0
	v_lshl_add_u64 v[8:9], s[12:13], 0, v[136:137]
	v_lshl_add_u64 v[6:7], s[12:13], 0, v[130:131]
	v_lshl_add_u64 v[4:5], s[14:15], 0, v[138:139]
	s_cmp_lg_u32 s17, 1
	v_lshl_add_u64 v[2:3], s[14:15], 0, v[132:133]
	s_cbranch_scc1 .LBB0_728
	s_barrier

.LBB0_730:
	s_add_i32 s38, s38, 1
	v_readlane_b32 s5, v243, 0
	s_mul_i32 s0, s38, s42
	s_mul_hi_u32 s1, s38, s5
	s_add_i32 s1, s1, s0
	s_mul_i32 s0, s38, s5
	s_mov_b64 s[22:23], s[12:13]
	s_add_u32 s12, s0, s94
	s_addc_u32 s13, s1, s43
	v_cmp_lt_i64_e64 s[0:1], s[12:13], v[146:147]
	s_mov_b64 s[24:25], s[14:15]
	s_and_b64 s[14:15], s[0:1], exec
	s_cselect_b32 s5, s12, 0
	s_ashr_i32 s14, s5, 31
	s_lshr_b32 s14, s14, 29
	s_add_i32 s14, s5, s14
	s_ashr_i32 s15, s14, 3
	s_and_b32 s14, s14, -8
	s_sub_i32 s5, s5, s14
	s_cmp_lt_i32 s5, 0
	s_cselect_b32 s14, s33, 0x183
	s_mul_i32 s5, s5, s14
	s_add_i32 s5, s5, s15
	s_mul_hi_i32 s14, s5, 0x2fa0be83
	s_lshr_b32 s15, s14, 31
	s_ashr_i32 s14, s14, 7
	s_add_i32 s14, s14, s15
	s_lshl_b32 s15, s14, 3
	s_sub_i32 s21, 36, s15
	s_min_i32 s21, s21, 8
	s_abs_i32 s57, s21
	v_cvt_f32_u32_e32 v2, s57
	s_mulk_i32 s14, 0x2b0
	s_mov_b32 s56, s4
	v_cmp_gt_i64_e32 vcc, s[12:13], v[144:145]
	v_rcp_iflag_f32_e32 v2, v2
	s_sub_i32 s4, s5, s14
	s_sub_i32 s13, 0, s57
	s_abs_i32 s12, s4
	v_mul_f32_e32 v2, 0x4f7ffffe, v2
	v_cvt_u32_f32_e32 v2, v2
	s_xor_b32 s5, s4, s21
	s_mov_b32 s55, s20
	s_ashr_i32 s5, s5, 31
	v_readfirstlane_b32 s14, v2
	s_mul_i32 s13, s13, s14
	s_mul_hi_u32 s13, s14, s13
	s_add_i32 s14, s14, s13
	s_mul_hi_u32 s13, s12, s14
	s_mul_i32 s14, s13, s57
	s_sub_i32 s12, s12, s14
	s_add_i32 s14, s13, 1
	s_sub_i32 s20, s12, s57
	s_cmp_ge_u32 s12, s57
	s_cselect_b32 s13, s14, s13
	s_cselect_b32 s12, s20, s12
	s_add_i32 s14, s13, 1
	s_cmp_ge_u32 s12, s57
	s_cselect_b32 s12, s14, s13
	s_xor_b32 s12, s12, s5
	s_sub_i32 s20, s12, s5
	s_mul_i32 s5, s20, s21
	s_sub_i32 s4, s4, s5
	s_add_i32 s4, s15, s4
	s_and_b32 s14, s94, 7
	s_lshr_b32 s15, s94, 3
	s_cmp_lt_u32 s38, 10
	s_cbranch_scc0 .Lp6ord_tail
	s_and_b32 s4, s15, 3
	s_lshl_b32 s5, s14, 2
	s_add_i32 s4, s4, s5
	s_lshr_b32 s20, s15, 2
	s_lshl_b32 s5, s38, 3
	s_add_i32 s20, s20, s5
	s_branch .Lp6ord_done
.Lp6ord_tail:
	s_sub_i32 s5, s38, 10
	s_lshl_b32 s5, s5, 5
	s_add_i32 s5, s5, s15
	s_mul_i32 s12, s14, 0x43
	s_add_i32 s5, s5, s12
	s_cmpk_lt_u32 s5, 0xc0
	s_cbranch_scc0 .Lp6ord_samp
	s_mul_hi_u32 s4, s5, 0x2aaaaaab
	s_mul_i32 s12, s4, 6
	s_sub_i32 s20, s5, s12
	s_addk_i32 s20, 0x50
	s_branch .Lp6ord_done
.Lp6ord_samp:
	s_sub_i32 s5, s5, 0xc0
	s_and_b32 s4, s5, 3
	s_addk_i32 s4, 0x20
	s_lshr_b32 s20, s5, 2
.Lp6ord_done:
	s_ashr_i32 s5, s4, 31
	s_lshl_b64 s[12:13], s[4:5], 21
	s_add_u32 s14, s27, s12
	s_addc_u32 s15, s28, s13
	s_and_b64 s[12:13], s[0:1], exec
	s_cselect_b32 s5, s15, s25
	s_cselect_b32 s57, s14, s24
	s_ashr_i32 s21, s20, 31
	s_lshl_b64 s[12:13], s[20:21], 21
	s_add_u32 s12, s29, s12
	s_addc_u32 s13, s30, s13
	s_and_b64 s[0:1], s[0:1], exec
	s_cselect_b32 s21, s13, s23
	s_cselect_b32 s58, s12, s22
	s_add_u32 s0, s24, 0x100080
	s_addc_u32 s1, s25, 0
	s_add_u32 s59, s22, 0x100
	v_mov_b32_e32 v2, 0
	s_addc_u32 s60, s23, 0
	s_mov_b32 s61, -2
	v_mov_b32_e32 v3, v2
	v_mov_b32_e32 v4, v2
	v_mov_b32_e32 v5, v2
	v_mov_b32_e32 v6, v2
	v_mov_b32_e32 v7, v2
	v_mov_b32_e32 v8, v2
	v_mov_b32_e32 v9, v2
	v_mov_b32_e32 v18, v2
	v_mov_b32_e32 v19, v2
	v_mov_b32_e32 v20, v2
	v_mov_b32_e32 v21, v2
	v_mov_b32_e32 v22, v2
	v_mov_b32_e32 v23, v2
	v_mov_b32_e32 v24, v2
	v_mov_b32_e32 v25, v2
	v_mov_b32_e32 v34, v2
	v_mov_b32_e32 v35, v2
	v_mov_b32_e32 v36, v2
	v_mov_b32_e32 v37, v2
	v_mov_b32_e32 v38, v2
	v_mov_b32_e32 v39, v2
	v_mov_b32_e32 v40, v2
	v_mov_b32_e32 v41, v2
	v_mov_b32_e32 v50, v2
	v_mov_b32_e32 v51, v2
	v_mov_b32_e32 v52, v2
	v_mov_b32_e32 v53, v2
	v_mov_b32_e32 v54, v2
	v_mov_b32_e32 v55, v2
	v_mov_b32_e32 v56, v2
	v_mov_b32_e32 v57, v2
	v_mov_b32_e32 v10, v2
	v_mov_b32_e32 v11, v2
	v_mov_b32_e32 v12, v2
	v_mov_b32_e32 v13, v2
	v_mov_b32_e32 v14, v2
	v_mov_b32_e32 v15, v2
	v_mov_b32_e32 v16, v2
	v_mov_b32_e32 v17, v2
	v_mov_b32_e32 v26, v2
	v_mov_b32_e32 v27, v2
	v_mov_b32_e32 v28, v2
	v_mov_b32_e32 v29, v2
	v_mov_b32_e32 v30, v2
	v_mov_b32_e32 v31, v2
	v_mov_b32_e32 v32, v2
	v_mov_b32_e32 v33, v2
	v_mov_b32_e32 v42, v2
	v_mov_b32_e32 v43, v2
	v_mov_b32_e32 v44, v2
	v_mov_b32_e32 v45, v2
	v_mov_b32_e32 v46, v2
	v_mov_b32_e32 v47, v2
	v_mov_b32_e32 v48, v2
	v_mov_b32_e32 v49, v2
	v_mov_b32_e32 v58, v2
	v_mov_b32_e32 v59, v2
	v_mov_b32_e32 v60, v2
	v_mov_b32_e32 v61, v2
	v_mov_b32_e32 v62, v2
	v_mov_b32_e32 v63, v2
	v_mov_b32_e32 v64, v2
	v_mov_b32_e32 v65, v2
	v_mov_b32_e32 v66, v2
	v_mov_b32_e32 v67, v2
	v_mov_b32_e32 v68, v2
	v_mov_b32_e32 v69, v2
	v_mov_b32_e32 v70, v2
	v_mov_b32_e32 v71, v2
	v_mov_b32_e32 v72, v2
	v_mov_b32_e32 v73, v2
	v_mov_b32_e32 v82, v2
	v_mov_b32_e32 v83, v2
	v_mov_b32_e32 v84, v2
	v_mov_b32_e32 v85, v2
	v_mov_b32_e32 v86, v2
	v_mov_b32_e32 v87, v2
	v_mov_b32_e32 v88, v2
	v_mov_b32_e32 v89, v2
	v_mov_b32_e32 v98, v2
	v_mov_b32_e32 v99, v2
	v_mov_b32_e32 v100, v2
	v_mov_b32_e32 v101, v2
	v_mov_b32_e32 v102, v2
	v_mov_b32_e32 v103, v2
	v_mov_b32_e32 v104, v2
	v_mov_b32_e32 v105, v2
	v_mov_b32_e32 v114, v2
	v_mov_b32_e32 v115, v2
	v_mov_b32_e32 v116, v2
	v_mov_b32_e32 v117, v2
	v_mov_b32_e32 v118, v2
	v_mov_b32_e32 v119, v2
	v_mov_b32_e32 v120, v2
	v_mov_b32_e32 v121, v2
	v_mov_b32_e32 v74, v2
	v_mov_b32_e32 v75, v2
	v_mov_b32_e32 v76, v2
	v_mov_b32_e32 v77, v2
	v_mov_b32_e32 v78, v2
	v_mov_b32_e32 v79, v2
	v_mov_b32_e32 v80, v2
	v_mov_b32_e32 v81, v2
	v_mov_b32_e32 v90, v2
	v_mov_b32_e32 v91, v2
	v_mov_b32_e32 v92, v2
	v_mov_b32_e32 v93, v2
	v_mov_b32_e32 v94, v2
	v_mov_b32_e32 v95, v2
	v_mov_b32_e32 v96, v2
	v_mov_b32_e32 v97, v2
	v_mov_b32_e32 v106, v2
	v_mov_b32_e32 v107, v2
	v_mov_b32_e32 v108, v2
	v_mov_b32_e32 v109, v2
	v_mov_b32_e32 v110, v2
	v_mov_b32_e32 v111, v2
	v_mov_b32_e32 v112, v2
	v_mov_b32_e32 v113, v2
	v_mov_b32_e32 v122, v2
	v_mov_b32_e32 v123, v2
	v_mov_b32_e32 v124, v2
	v_mov_b32_e32 v125, v2
	v_mov_b32_e32 v126, v2
	v_mov_b32_e32 v127, v2
	v_mov_b32_e32 v128, v2
	v_mov_b32_e32 v129, v2
